# P1 sample in_proj tiles: fragments staged through LDS with coalesced LDS-DMA pieces (source-side XOR swizzle) and ds_read_b128 in MFMA layout instead of 24 row-per-lane global loads per wave; same MFM
# speedup vs baseline: 1.0091x; 1.0087x over previous
.LBB0_125:
	s_mul_hi_i32 s28, s61, 0x2aaaaaab
	s_lshr_b32 s29, s28, 31
	s_ashr_i32 s28, s28, 3
	s_add_i32 s31, s28, s29
	s_mul_i32 s28, s31, 0xffffffd0
	s_add_i32 s63, s61, s28
	s_mul_i32 s28, s31, 0xfffff400
	s_add_i32 s30, s27, s28
	s_and_b32 s28, s30, 0xffffff00
	s_and_b32 s29, s54, 0x60
	s_or_b32 s28, s28, s29
	s_ashr_i32 s29, s28, 31
	s_lshl_b64 s[34:35], s[28:29], 11
	s_add_u32 s34, s3, s34
	s_addc_u32 s35, s39, s35
	s_bitset1_b32 s28, 7
	s_ashr_i32 s29, s28, 31
	v_mov_b32_e32 v37, v228
	s_lshl_b64 s[28:29], s[28:29], 11
	s_add_u32 s36, s3, s28
	v_and_b32_e32 v122, 31, v37
	v_ashrrev_i32_e32 v123, 5, v37
	s_addc_u32 s37, s39, s29
	s_lshl_b32 s28, s31, 5
	s_ashr_i32 s29, s28, 31
	s_lshl_b64 s[64:65], s[28:29], 11
	s_add_u32 s64, s58, s64
	s_addc_u32 s65, s59, s65
	s_mov_b32 s101, m0
	s_mul_i32 s100, s2, 0x180
	v_lshrrev_b32_e32 v14, 2, v37
	v_bfe_u32 v15, v37, 4, 2
	v_lshlrev_b32_e32 v14, 11, v14
	v_xor_b32_e32 v15, v15, v37
	v_bfe_u32 v16, v122, 2, 2
	v_and_b32_e32 v15, 3, v15
	v_xor_b32_e32 v16, v16, v123
	v_lshl_or_b32 v14, v15, 4, v14
	v_lshlrev_b32_e32 v16, 4, v16
	v_lshl_or_b32 v15, v122, 6, v16
	v_add_u32_e32 v15, s100, v15
	v_xor_b32_e32 v16, 32, v15
	s_add_u32 s98, s34, s0
	s_addc_u32 s99, s35, 0
	s_add_i32 m0, s100, 0x0
	s_nop 0
	global_load_lds_dwordx4 v14, s[98:99]
	s_add_u32 s98, s34, s0
	s_addc_u32 s99, s35, 0
	s_add_u32 s98, s98, 0x8000
	s_addc_u32 s99, s99, 0
	s_add_i32 m0, s100, 0x400
	s_nop 0
	global_load_lds_dwordx4 v14, s[98:99]
	s_add_u32 s98, s36, s0
	s_addc_u32 s99, s37, 0
	s_add_i32 m0, s100, 0x800
	s_nop 0
	global_load_lds_dwordx4 v14, s[98:99]
	s_add_u32 s98, s36, s0
	s_addc_u32 s99, s37, 0
	s_add_u32 s98, s98, 0x8000
	s_addc_u32 s99, s99, 0
	s_add_i32 m0, s100, 0xc00
	s_nop 0
	global_load_lds_dwordx4 v14, s[98:99]
	s_add_u32 s98, s64, s0
	s_addc_u32 s99, s65, 0
	s_add_u32 s98, s98, 0x2000000
	s_addc_u32 s99, s99, 0
	s_add_i32 m0, s100, 0x1000
	s_nop 0
	global_load_lds_dwordx4 v14, s[98:99]
	s_add_u32 s98, s64, s0
	s_addc_u32 s99, s65, 0
	s_add_u32 s98, s98, 0x2008000
	s_addc_u32 s99, s99, 0
	s_add_i32 m0, s100, 0x1400
	s_nop 0
	global_load_lds_dwordx4 v14, s[98:99]
	s_add_u32 s98, s34, s0
	s_addc_u32 s99, s35, 0
	s_add_u32 s98, s98, 0x40
	s_addc_u32 s99, s99, 0
	s_add_i32 m0, s100, 0x1800
	s_nop 0
	global_load_lds_dwordx4 v14, s[98:99]
	s_add_u32 s98, s34, s0
	s_addc_u32 s99, s35, 0
	s_add_u32 s98, s98, 0x8040
	s_addc_u32 s99, s99, 0
	s_add_i32 m0, s100, 0x1c00
	s_nop 0
	global_load_lds_dwordx4 v14, s[98:99]
	s_add_u32 s98, s36, s0
	s_addc_u32 s99, s37, 0
	s_add_u32 s98, s98, 0x40
	s_addc_u32 s99, s99, 0
	s_add_i32 m0, s100, 0x2000
	s_nop 0
	global_load_lds_dwordx4 v14, s[98:99]
	s_add_u32 s98, s36, s0
	s_addc_u32 s99, s37, 0
	s_add_u32 s98, s98, 0x8040
	s_addc_u32 s99, s99, 0
	s_add_i32 m0, s100, 0x2400
	s_nop 0
	global_load_lds_dwordx4 v14, s[98:99]
	s_add_u32 s98, s64, s0
	s_addc_u32 s99, s65, 0
	s_add_u32 s98, s98, 0x2000040
	s_addc_u32 s99, s99, 0
	s_add_i32 m0, s100, 0x2800
	s_nop 0
	global_load_lds_dwordx4 v14, s[98:99]
	s_add_u32 s98, s64, s0
	s_addc_u32 s99, s65, 0
	s_add_u32 s98, s98, 0x2008040
	s_addc_u32 s99, s99, 0
	s_add_i32 m0, s100, 0x2c00
	s_nop 0
	global_load_lds_dwordx4 v14, s[98:99]
	s_waitcnt vmcnt(6)
	ds_read_b128 v[2:5], v15
	ds_read_b128 v[6:9], v15 offset:2048
	ds_read_b128 v[10:13], v15 offset:4096
	ds_read_b128 v[38:41], v16
	ds_read_b128 v[42:45], v16 offset:2048
	ds_read_b128 v[46:49], v16 offset:4096
	s_waitcnt lgkmcnt(0)
	s_add_u32 s98, s34, s0
	s_addc_u32 s99, s35, 0
	s_add_u32 s98, s98, 0x80
	s_addc_u32 s99, s99, 0
	s_add_i32 m0, s100, 0x0
	s_nop 0
	global_load_lds_dwordx4 v14, s[98:99]
	s_add_u32 s98, s34, s0
	s_addc_u32 s99, s35, 0
	s_add_u32 s98, s98, 0x8080
	s_addc_u32 s99, s99, 0
	s_add_i32 m0, s100, 0x400
	s_nop 0
	global_load_lds_dwordx4 v14, s[98:99]
	s_add_u32 s98, s36, s0
	s_addc_u32 s99, s37, 0
	s_add_u32 s98, s98, 0x80
	s_addc_u32 s99, s99, 0
	s_add_i32 m0, s100, 0x800
	s_nop 0
	global_load_lds_dwordx4 v14, s[98:99]
	s_add_u32 s98, s36, s0
	s_addc_u32 s99, s37, 0
	s_add_u32 s98, s98, 0x8080
	s_addc_u32 s99, s99, 0
	s_add_i32 m0, s100, 0xc00
	s_nop 0
	global_load_lds_dwordx4 v14, s[98:99]
	s_add_u32 s98, s64, s0
	s_addc_u32 s99, s65, 0
	s_add_u32 s98, s98, 0x2000080
	s_addc_u32 s99, s99, 0
	s_add_i32 m0, s100, 0x1000
	s_nop 0
	global_load_lds_dwordx4 v14, s[98:99]
	s_add_u32 s98, s64, s0
	s_addc_u32 s99, s65, 0
	s_add_u32 s98, s98, 0x2008080
	s_addc_u32 s99, s99, 0
	s_add_i32 m0, s100, 0x1400
	s_nop 0
	global_load_lds_dwordx4 v14, s[98:99]
	s_waitcnt vmcnt(6)
	ds_read_b128 v[54:57], v15 offset:6144
	ds_read_b128 v[62:65], v15 offset:8192
	ds_read_b128 v[50:53], v15 offset:10240
	ds_read_b128 v[58:61], v16 offset:6144
	ds_read_b128 v[66:69], v16 offset:8192
	ds_read_b128 v[70:73], v16 offset:10240
	s_waitcnt lgkmcnt(0)
	s_add_u32 s98, s34, s0
	s_addc_u32 s99, s35, 0
	s_add_u32 s98, s98, 0xc0
	s_addc_u32 s99, s99, 0
	s_add_i32 m0, s100, 0x1800
	s_nop 0
	global_load_lds_dwordx4 v14, s[98:99]
	s_add_u32 s98, s34, s0
	s_addc_u32 s99, s35, 0
	s_add_u32 s98, s98, 0x80c0
	s_addc_u32 s99, s99, 0
	s_add_i32 m0, s100, 0x1c00
	s_nop 0
	global_load_lds_dwordx4 v14, s[98:99]
	s_add_u32 s98, s36, s0
	s_addc_u32 s99, s37, 0
	s_add_u32 s98, s98, 0xc0
	s_addc_u32 s99, s99, 0
	s_add_i32 m0, s100, 0x2000
	s_nop 0
	global_load_lds_dwordx4 v14, s[98:99]
	s_add_u32 s98, s36, s0
	s_addc_u32 s99, s37, 0
	s_add_u32 s98, s98, 0x80c0
	s_addc_u32 s99, s99, 0
	s_add_i32 m0, s100, 0x2400
	s_nop 0
	global_load_lds_dwordx4 v14, s[98:99]
	s_add_u32 s98, s64, s0
	s_addc_u32 s99, s65, 0
	s_add_u32 s98, s98, 0x20000c0
	s_addc_u32 s99, s99, 0
	s_add_i32 m0, s100, 0x2800
	s_nop 0
	global_load_lds_dwordx4 v14, s[98:99]
	s_add_u32 s98, s64, s0
	s_addc_u32 s99, s65, 0
	s_add_u32 s98, s98, 0x20080c0
	s_addc_u32 s99, s99, 0
	s_add_i32 m0, s100, 0x2c00
	s_nop 0
	global_load_lds_dwordx4 v14, s[98:99]
	s_waitcnt vmcnt(6)
	ds_read_b128 v[78:81], v15
	ds_read_b128 v[86:89], v15 offset:2048
	ds_read_b128 v[74:77], v15 offset:4096
	ds_read_b128 v[82:85], v16
	ds_read_b128 v[90:93], v16 offset:2048
	ds_read_b128 v[94:97], v16 offset:4096
	s_waitcnt vmcnt(0)
	ds_read_b128 v[102:105], v15 offset:6144
	ds_read_b128 v[110:113], v15 offset:8192
	ds_read_b128 v[98:101], v15 offset:10240
	ds_read_b128 v[106:109], v16 offset:6144
	ds_read_b128 v[114:117], v16 offset:8192
	ds_read_b128 v[118:121], v16 offset:10240
	s_mov_b32 m0, s101
	s_waitcnt lgkmcnt(0)
	v_mfma_f32_32x32x16_bf16 v[18:33], v[2:5], v[10:13], 0
	v_or_b32_e32 v34, s2, v122
	v_mul_lo_u32 v34, v34, s57
	s_ashr_i32 s64, s63, 3
	v_mfma_f32_32x32x16_bf16 v[2:17], v[6:9], v[10:13], 0
	v_mfma_f32_32x32x16_bf16 v[18:33], v[38:41], v[46:49], v[18:33]
	v_lshlrev_b32_e32 v38, 4, v123
	v_add3_u32 v34, 0, v34, v38
	v_mfma_f32_32x32x16_bf16 v[2:17], v[42:45], v[46:49], v[2:17]
	v_mfma_f32_32x32x16_bf16 v[18:33], v[54:57], v[50:53], v[18:33]
	v_mfma_f32_32x32x16_bf16 v[2:17], v[62:65], v[50:53], v[2:17]
	v_mfma_f32_32x32x16_bf16 v[18:33], v[58:61], v[70:73], v[18:33]
	v_mfma_f32_32x32x16_bf16 v[2:17], v[66:69], v[70:73], v[2:17]
	v_mfma_f32_32x32x16_bf16 v[18:33], v[78:81], v[74:77], v[18:33]
	v_mfma_f32_32x32x16_bf16 v[2:17], v[86:89], v[74:77], v[2:17]
	v_mfma_f32_32x32x16_bf16 v[18:33], v[82:85], v[94:97], v[18:33]
	v_mfma_f32_32x32x16_bf16 v[2:17], v[90:93], v[94:97], v[2:17]
	v_mfma_f32_32x32x16_bf16 v[18:33], v[102:105], v[98:101], v[18:33]
	v_mfma_f32_32x32x16_bf16 v[2:17], v[110:113], v[98:101], v[2:17]
	v_mfma_f32_32x32x16_bf16 v[18:33], v[106:109], v[118:121], v[18:33]
	v_mfma_f32_32x32x16_bf16 v[2:17], v[114:117], v[118:121], v[2:17]
	s_nop 10
	s_barrier
	ds_write_b128 v34, v[18:21]
	ds_write_b128 v34, v[2:5] offset:128
	ds_write_b128 v34, v[22:25] offset:32
	ds_write_b128 v34, v[6:9] offset:160
	ds_write_b128 v34, v[26:29] offset:64
	ds_write_b128 v34, v[10:13] offset:192
	ds_write_b128 v34, v[30:33] offset:96
	ds_write_b128 v34, v[14:17] offset:224
	v_add_u32_e32 v2, s26, v37
	v_ashrrev_i32_e32 v13, 4, v2
	v_lshlrev_b32_e32 v2, 2, v37
	v_and_b32_e32 v20, 60, v2
	v_lshlrev_b32_e32 v12, 2, v20
	v_mul_lo_u32 v2, v13, s57
	v_add3_u32 v21, 0, v12, v2
	s_waitcnt lgkmcnt(0)
	s_barrier
	ds_read_b128 v[2:5], v21
	ds_read_b128 v[6:9], v21 offset:8704
	ds_read_b128 v[14:17], v21 offset:17408
	s_waitcnt lgkmcnt(2)
	v_pk_add_f32 v[4:5], v[4:5], 0 op_sel_hi:[1,0]
	v_pk_add_f32 v[10:11], v[2:3], 0 op_sel_hi:[1,0]
	s_waitcnt lgkmcnt(1)
	v_pk_add_f32 v[8:9], v[4:5], v[8:9]
	ds_read_b128 v[2:5], v21 offset:26112
	v_pk_add_f32 v[10:11], v[10:11], v[6:7]
	s_waitcnt lgkmcnt(1)
	v_pk_add_f32 v[16:17], v[8:9], v[16:17]
	ds_read_b128 v[6:9], v21 offset:34816
	v_pk_add_f32 v[10:11], v[10:11], v[14:15]
	s_waitcnt lgkmcnt(1)
	v_pk_add_f32 v[14:15], v[16:17], v[4:5]
	v_pk_add_f32 v[16:17], v[10:11], v[2:3]
	ds_read_b128 v[2:5], v21 offset:43520
	s_waitcnt lgkmcnt(1)
	v_pk_add_f32 v[18:19], v[14:15], v[8:9]
	ds_read_b128 v[8:11], v21 offset:52224
	v_pk_add_f32 v[6:7], v[16:17], v[6:7]
	ds_read_b128 v[14:17], v21 offset:60928
	s_waitcnt lgkmcnt(2)
	v_pk_add_f32 v[2:3], v[6:7], v[2:3]
	v_add_u32_e32 v6, s28, v13
	v_pk_add_f32 v[4:5], v[18:19], v[4:5]
	v_ashrrev_i32_e32 v7, 31, v6
	s_waitcnt lgkmcnt(1)
	v_pk_add_f32 v[4:5], v[4:5], v[10:11]
	v_pk_add_f32 v[2:3], v[2:3], v[8:9]
	v_lshlrev_b64 v[10:11], 9, v[6:7]
	s_and_b32 s28, s30, 0x1c0
	s_waitcnt lgkmcnt(0)
	v_pk_add_f32 v[4:5], v[4:5], v[16:17]
	v_pk_add_f32 v[2:3], v[2:3], v[14:15]
	v_or3_b32 v10, v10, s28, v20
	s_cmp_gt_i32 s64, 1
	s_mov_b64 s[28:29], -1
	s_barrier
	s_cbranch_scc0 .LBB0_138
	s_mov_b64 s[36:37], -1
	s_mov_b64 s[28:29], 0
	s_cmp_lt_i32 s64, 4
	s_mov_b64 s[30:31], 0
	s_mov_b64 s[34:35], 0
	s_cbranch_scc1 .LBB0_131
	s_cmp_lg_u32 s64, 4
	s_mov_b64 s[30:31], -1
	s_cselect_b64 s[34:35], -1, 0
	s_cbranch_execz .LBB0_132
